# peel first K iteration of G3 GEMM loop: first MFMA into each accumulator takes C=0, accumulator zeroing moves dropped
# speedup vs baseline: 1.0113x; 1.0044x over previous
.LBB0_243:
	s_lshl_b32 s4, s34, 2
	v_readlane_b32 s40, v254, 37
	v_readlane_b32 s41, v254, 38
	s_add_u32 s4, s40, s4
	s_addc_u32 s5, s41, 0
	s_add_u32 s89, s4, 0x18000
	s_addc_u32 s90, s5, 0
	s_add_u32 s52, s40, 0xf600000
	v_lshrrev_b32_e32 v0, 1, v170
	s_addc_u32 s53, s41, 0
	v_and_b32_e32 v0, 24, v0
	s_lshl_b32 s2, s2, 5
	v_lshlrev_b32_e32 v10, 6, v189
	v_lshlrev_b32_e32 v11, 1, v0
	s_movk_i32 s4, 0x3c0
	s_and_b32 s34, s2, 0x60
	s_add_i32 m0, s21, 0x18000
	v_lshl_add_u64 v[8:9], v[8:9], 0, s[14:15]
	v_lshl_or_b32 v171, s3, 6, v189
	v_and_or_b32 v10, v10, s4, v11
	s_lshl_b32 s3, s3, 13
	v_lshlrev_b32_e32 v12, 2, v189
	v_or_b32_e32 v11, v11, v188
	s_lshl_b32 s2, s34, 7
	s_waitcnt vmcnt(2)
	s_barrier
	global_load_lds_dwordx4 v[8:9], off
	v_lshl_add_u64 v[6:7], v[6:7], 0, s[14:15]
	s_add_i32 m0, s21, 0x1a000
	s_add_i32 s91, s21, 0x8000
	s_add_i32 s92, s21, 0xa000
	v_and_b32_e32 v13, 32, v12
	v_bitop3_b32 v188, s2, v11, v190 bitop3:0xf6
	global_load_lds_dwordx4 v[6:7], off
	v_lshl_add_u64 v[2:3], v[2:3], 0, s[14:15]
	s_mov_b32 m0, s91
	s_add_u32 s2, s74, 0x40080
	v_bitop3_b32 v10, v10, s3, v13 bitop3:0xde
	global_load_lds_dwordx4 v[2:3], off
	v_lshl_add_u64 v[2:3], v[4:5], 0, s[14:15]
	s_mov_b32 m0, s92
	s_addc_u32 s3, s75, 0
	global_load_lds_dwordx4 v[2:3], off
	s_add_i32 m0, s21, 0x1c000
	v_lshl_add_u64 v[2:3], s[2:3], 0, v[164:165]
	global_load_lds_dwordx4 v[2:3], off
	s_add_i32 m0, s21, 0x1e000
	s_cmpk_lt_u32 s29, 0x100
	v_lshl_add_u64 v[2:3], s[2:3], 0, v[174:175]
	s_cselect_b64 s[54:55], -1, 0
	s_and_b32 s2, s29, 0xffffff00
	s_add_i32 s2, s2, 0
	s_lshr_b32 s95, s10, 3
	global_load_lds_dwordx4 v[2:3], off
	s_add_i32 s2, s2, 0x20800
	s_ashr_i32 s93, s94, 31
	s_mov_b32 s42, s94
	s_and_b32 s40, s10, 4
	s_add_i32 s96, s95, 1
	v_mov_b32_e32 v2, 0x98
	s_cmpk_gt_i32 s94, 0x7f
	v_sub_co_u32_e32 v4, vcc, s42, v2
	s_cselect_b64 s[58:59], -1, 0
	s_xor_b64 s[60:61], vcc, -1
	s_cmpk_gt_u32 s94, 0xc3
	v_add_u32_e32 v189, s2, v12
	s_cselect_b64 s[2:3], -1, 0
	v_writelane_b32 v255, s2, 29
	s_cmpk_gt_u32 s94, 0xf7
	s_mov_b32 s11, s17
	v_writelane_b32 v255, s3, 30
	s_cselect_b64 s[2:3], -1, 0
	v_writelane_b32 v255, s2, 31
	s_cmpk_lt_u32 s94, 0xcc
	s_cselect_b64 s[62:63], -1, 0
	v_writelane_b32 v255, s3, 32
	s_cmpk_lt_u32 s94, 0xf4
	s_movk_i32 s2, 0xffd0
	s_cselect_b32 s2, s2, 0xffffffa4
	s_add_i32 s2, s2, s94
	s_add_i32 s16, s2, 0x400
	v_mov_b64_e32 v[2:3], s[10:11]
	s_and_b32 s2, s2, 7
	v_mov_b32_e32 v5, s40
	v_cmp_ge_u64_e64 s[4:5], s[16:17], v[2:3]
	v_sub_co_u32_e32 v2, vcc, s2, v5
	s_nop 0
	v_readfirstlane_b32 s3, v2
	s_mul_i32 s97, s96, s40
	s_mul_i32 s3, s3, s95
	s_lshr_b32 s29, s16, 3
	s_add_i32 s71, s97, s3
	s_mul_i32 s73, s96, s2
	s_add_i32 s2, s94, 0x134
	v_writelane_b32 v254, s4, 46
	s_cmp_lt_i32 s2, s10
	s_waitcnt vmcnt(6)
	s_mov_b32 s66, s94
	v_writelane_b32 v254, s5, 47
	s_cselect_b64 s[4:5], -1, 0
	v_writelane_b32 v254, s4, 48
	s_mov_b32 s67, s17
	v_cmp_eq_u32_e64 s[44:45], 0, v206
	v_writelane_b32 v254, s5, 49
	s_and_b32 s4, s2, 7
	v_sub_co_u32_e64 v2, s[2:3], s4, v5
	s_nop 0
	v_readfirstlane_b32 s5, v2
	s_mul_i32 s5, s5, s95
	s_add_i32 s76, s97, s5
	s_mul_i32 s77, s96, s4
	v_readfirstlane_b32 s4, v4
	s_cmp_gt_u32 s4, 21
	s_cselect_b32 s25, 0x41, 64
	s_add_i32 s4, s94, 0xffffff52
	v_mov_b32_e32 v2, s4
	v_cmp_gt_u32_e64 s[4:5], 22, v4
	v_mov_b32_e32 v192, s72
	v_mov_b64_e32 v[130:131], s[74:75]
	v_cndmask_b32_e64 v190, v2, v4, s[4:5]
	s_add_i32 s4, s94, 0xffffff80
	s_lshr_b32 s4, s4, 3
	s_add_i32 s16, s4, 2
	s_lshl_b64 s[4:5], s[16:17], 8
	s_add_u32 s4, s4, s94
	s_addc_u32 s5, s5, 0
	s_or_b32 s4, s4, 0xf8
	v_mov_b64_e32 v[2:3], s[10:11]
	v_cmp_ge_u64_e64 s[42:43], s[4:5], v[2:3]
	s_lshr_b32 s16, s4, 3
	v_sub_co_u32_e64 v2, s[4:5], s70, v5
	s_nop 0
	v_readfirstlane_b32 s41, v2
	s_mul_i32 s41, s41, s95
	s_add_i32 s78, s97, s41
	s_and_b64 s[68:69], vcc, exec
	s_cselect_b32 s68, s73, s71
	s_add_i32 s68, s68, s29
	s_mul_hi_u32 s29, s68, 0xba2e8ba3
	s_lshr_b32 s29, s29, 7
	s_lshl_b32 s69, s29, 3
	s_sub_i32 s71, 64, s69
	s_mulk_i32 s29, 0xb0
	s_min_i32 s71, s71, 8
	s_sub_i32 s29, s68, s29
	s_and_b64 s[2:3], s[2:3], exec
	s_cselect_b32 s2, s77, s76
	s_add_i32 s2, s2, 63
	s_mul_hi_u32 s3, s2, 0xba2e8ba3
	s_lshr_b32 s3, s3, 7
	s_lshl_b32 s68, s3, 3
	s_sub_i32 s73, 64, s68
	s_mulk_i32 s3, 0xb0
	s_min_i32 s73, s73, 8
	s_sub_i32 s76, s2, s3
	s_mul_i32 s70, s96, s70
	s_and_b64 s[2:3], s[4:5], exec
	s_cselect_b32 s2, s70, s78
	s_abs_i32 s4, s71
	v_cvt_f32_u32_e32 v2, s4
	s_sub_i32 s77, 0, s4
	s_add_i32 s2, s2, s16
	s_mul_hi_u32 s3, s2, 0xba2e8ba3
	v_rcp_iflag_f32_e32 v2, v2
	s_abs_i32 s70, s29
	s_lshr_b32 s3, s3, 7
	s_lshl_b32 s5, s3, 3
	v_mul_f32_e32 v2, 0x4f7ffffe, v2
	v_cvt_u32_f32_e32 v2, v2
	s_mulk_i32 s3, 0xb0
	s_sub_i32 s16, 64, s5
	s_sub_i32 s2, s2, s3
	v_readfirstlane_b32 s78, v2
	s_mul_i32 s77, s77, s78
	s_mul_hi_u32 s77, s78, s77
	s_add_i32 s78, s78, s77
	s_mul_hi_u32 s77, s70, s78
	s_mul_i32 s78, s77, s4
	s_xor_b32 s3, s29, s71
	s_sub_i32 s70, s70, s78
	s_min_i32 s16, s16, 8
	s_ashr_i32 s3, s3, 31
	s_add_i32 s78, s77, 1
	s_sub_i32 s79, s70, s4
	s_cmp_ge_u32 s70, s4
	s_cselect_b32 s77, s78, s77
	s_cselect_b32 s70, s79, s70
	s_add_i32 s78, s77, 1
	s_cmp_ge_u32 s70, s4
	s_cselect_b32 s4, s78, s77
	s_abs_i32 s77, s73
	v_cvt_f32_u32_e32 v2, s77
	s_xor_b32 s4, s4, s3
	s_sub_i32 s70, s4, s3
	s_mul_i32 s3, s70, s71
	v_rcp_iflag_f32_e32 v2, v2
	s_sub_i32 s3, s29, s3
	s_add_i32 s65, s69, s3
	s_sub_i32 s29, 0, s77
	v_mul_f32_e32 v2, 0x4f7ffffe, v2
	v_cvt_u32_f32_e32 v2, v2
	s_abs_i32 s4, s76
	s_xor_b32 s3, s76, s73
	s_ashr_i32 s3, s3, 31
	v_readfirstlane_b32 s69, v2
	s_mul_i32 s29, s29, s69
	s_mul_hi_u32 s29, s69, s29
	s_add_i32 s69, s69, s29
	s_mul_hi_u32 s29, s4, s69
	s_mul_i32 s69, s29, s77
	s_sub_i32 s4, s4, s69
	s_add_i32 s69, s29, 1
	s_sub_i32 s71, s4, s77
	s_cmp_ge_u32 s4, s77
	s_cselect_b32 s29, s69, s29
	s_cselect_b32 s4, s71, s4
	s_add_i32 s69, s29, 1
	s_cmp_ge_u32 s4, s77
	s_cselect_b32 s4, s69, s29
	s_abs_i32 s29, s16
	v_cvt_f32_u32_e32 v2, s29
	s_xor_b32 s4, s4, s3
	s_sub_i32 s71, s4, s3
	s_mul_i32 s3, s71, s73
	v_rcp_iflag_f32_e32 v2, v2
	s_sub_i32 s3, s76, s3
	s_add_i32 s3, s68, s3
	s_sub_i32 s68, 0, s29
	v_mul_f32_e32 v2, 0x4f7ffffe, v2
	v_cvt_u32_f32_e32 v2, v2
	s_abs_i32 s4, s2
	v_writelane_b32 v254, s3, 62
	s_xor_b32 s3, s2, s16
	v_readfirstlane_b32 s69, v2
	s_mul_i32 s68, s68, s69
	s_mul_hi_u32 s68, s69, s68
	s_add_i32 s69, s69, s68
	s_mul_hi_u32 s68, s4, s69
	s_mul_i32 s69, s68, s29
	s_sub_i32 s4, s4, s69
	s_ashr_i32 s3, s3, 31
	s_add_i32 s69, s68, 1
	s_sub_i32 s73, s4, s29
	s_cmp_ge_u32 s4, s29
	s_cselect_b32 s68, s69, s68
	s_cselect_b32 s4, s73, s4
	s_add_i32 s69, s68, 1
	s_cmp_ge_u32 s4, s29
	s_cselect_b32 s4, s69, s68
	s_xor_b32 s4, s4, s3
	s_sub_i32 s68, s4, s3
	s_mul_i32 s3, s68, s16
	s_sub_i32 s2, s2, s3
	v_mov_b32_e32 v2, 0
	s_mov_b32 s41, 0
	s_add_i32 s69, s5, s2
	v_add_u32_e32 v191, 0, v10
	s_lshl_b32 s4, s34, 1
	v_lshlrev_b32_e32 v0, 1, v0
	s_barrier
	s_branch .LBB0_246
.LBB0_244:
	s_mov_b32 s22, s72
	v_mov_b32_e32 v192, v132
	v_mov_b64_e32 v[130:131], v[134:135]
	s_mov_b64 s[8:9], s[80:81]
	s_mov_b32 s41, s74

.Ltb_g3_skip:
	s_mov_b64 s[2:3], 0
	s_lshl_b32 s16, s34, 7
	s_add_u32 s73, s8, s16
	s_addc_u32 s75, s9, 0
	s_add_u32 vcc_lo, s73, 0x100
	s_addc_u32 vcc_hi, s75, 0
	s_and_b64 s[86:87], s[2:3], exec
	s_cselect_b32 s87, s5, vcc_hi
	s_cselect_b32 s86, s29, vcc_lo
	v_lshl_add_u64 v[136:137], v[130:131], 0, s[16:17]
	s_mov_b64 vcc, 0x100
	s_add_i32 s16, 0, 0x10000
	v_lshl_add_u64 v[136:137], v[136:137], 0, vcc
	v_add_u32_e32 v139, s16, v188
	s_add_i32 vcc_lo, 0, 0x14000
	ds_read_b128 v[140:143], v139
	ds_read_b128 v[150:153], v139 offset:1024
	ds_read_b128 v[154:157], v139 offset:2048
	ds_read_b128 v[158:161], v139 offset:3072
	v_add_u32_e32 v139, vcc_lo, v188
	ds_read_b128 v[176:179], v139
	ds_read_b128 v[180:183], v139 offset:1024
	ds_read_b128 v[184:187], v139 offset:2048
	ds_read_b128 v[194:197], v139 offset:3072
	v_cndmask_b32_e64 v137, v137, v133, s[2:3]
	v_cndmask_b32_e64 v136, v136, v138, s[2:3]
	s_add_u32 s2, s73, 0x40080
	s_addc_u32 s3, s75, 0
	v_lshl_add_u64 v[144:145], s[2:3], 0, v[162:163]
	s_add_i32 m0, s21, 0xc000
	ds_read_b128 v[198:201], v191
	ds_read_b128 v[202:205], v191 offset:1024
	ds_read_b128 v[214:217], v191 offset:2048
	ds_read_b128 v[218:221], v191 offset:3072
	ds_read_b128 v[222:225], v191 offset:4096
	ds_read_b128 v[226:229], v191 offset:5120
	ds_read_b128 v[230:233], v191 offset:6144
	ds_read_b128 v[234:237], v191 offset:7168
	global_load_lds_dwordx4 v[144:145], off
	v_lshl_add_u64 v[144:145], s[2:3], 0, v[172:173]
	s_add_i32 m0, s21, 0xe000
	s_nop 0
	global_load_lds_dwordx4 v[144:145], off
	s_waitcnt vmcnt(8)
	s_waitcnt lgkmcnt(0)
	s_barrier
	s_setprio 1
	s_waitcnt lgkmcnt(0)
	v_mfma_f32_16x16x32_bf16 v[126:129], v[140:143], v[198:201], 0
	v_mfma_f32_16x16x32_bf16 v[122:125], v[154:157], v[198:201], 0
	v_mfma_f32_16x16x32_bf16 v[118:121], v[140:143], v[214:217], 0
	v_mfma_f32_16x16x32_bf16 v[114:117], v[154:157], v[214:217], 0
	v_mfma_f32_16x16x32_bf16 v[110:113], v[140:143], v[222:225], 0
	v_mfma_f32_16x16x32_bf16 v[106:109], v[154:157], v[222:225], 0
	v_mfma_f32_16x16x32_bf16 v[102:105], v[140:143], v[230:233], 0
	v_mfma_f32_16x16x32_bf16 v[98:101], v[154:157], v[230:233], 0
	v_mfma_f32_16x16x32_bf16 v[126:129], v[150:153], v[202:205], v[126:129]
	v_mfma_f32_16x16x32_bf16 v[122:125], v[158:161], v[202:205], v[122:125]
	v_mfma_f32_16x16x32_bf16 v[118:121], v[150:153], v[218:221], v[118:121]
	v_mfma_f32_16x16x32_bf16 v[114:117], v[158:161], v[218:221], v[114:117]
	v_mfma_f32_16x16x32_bf16 v[110:113], v[150:153], v[226:229], v[110:113]
	v_mfma_f32_16x16x32_bf16 v[106:109], v[158:161], v[226:229], v[106:109]
	v_mfma_f32_16x16x32_bf16 v[102:105], v[150:153], v[234:237], v[102:105]
	v_mfma_f32_16x16x32_bf16 v[98:101], v[158:161], v[234:237], v[98:101]
	s_setprio 0
	s_setprio 1
	v_mfma_f32_16x16x32_bf16 v[94:97], v[176:179], v[198:201], 0
	v_mfma_f32_16x16x32_bf16 v[90:93], v[184:187], v[198:201], 0
	v_mfma_f32_16x16x32_bf16 v[86:89], v[176:179], v[214:217], 0
	v_mfma_f32_16x16x32_bf16 v[82:85], v[184:187], v[214:217], 0
	v_mfma_f32_16x16x32_bf16 v[78:81], v[176:179], v[222:225], 0
	v_mfma_f32_16x16x32_bf16 v[74:77], v[184:187], v[222:225], 0
	v_mfma_f32_16x16x32_bf16 v[70:73], v[176:179], v[230:233], 0
	v_mfma_f32_16x16x32_bf16 v[66:69], v[184:187], v[230:233], 0
	v_mfma_f32_16x16x32_bf16 v[94:97], v[180:183], v[202:205], v[94:97]
	v_mfma_f32_16x16x32_bf16 v[90:93], v[194:197], v[202:205], v[90:93]
	v_mfma_f32_16x16x32_bf16 v[86:89], v[180:183], v[218:221], v[86:89]
	v_mfma_f32_16x16x32_bf16 v[82:85], v[194:197], v[218:221], v[82:85]
	v_mfma_f32_16x16x32_bf16 v[78:81], v[180:183], v[226:229], v[78:81]
	v_mfma_f32_16x16x32_bf16 v[74:77], v[194:197], v[226:229], v[74:77]
	v_mfma_f32_16x16x32_bf16 v[70:73], v[180:183], v[234:237], v[70:73]
	v_mfma_f32_16x16x32_bf16 v[66:69], v[194:197], v[234:237], v[66:69]
	s_setprio 0
	s_barrier
	s_add_i32 s2, s16, s20
	v_lshl_add_u64 v[144:145], v[136:137], 0, v[164:165]
	s_mov_b32 m0, s2
	ds_read_b128 v[198:201], v191 offset:16384
	ds_read_b128 v[202:205], v191 offset:17408
	ds_read_b128 v[214:217], v191 offset:18432
	ds_read_b128 v[218:221], v191 offset:19456
	ds_read_b128 v[222:225], v191 offset:20480
	ds_read_b128 v[226:229], v191 offset:21504
	ds_read_b128 v[230:233], v191 offset:22528
	ds_read_b128 v[234:237], v191 offset:23552
	global_load_lds_dwordx4 v[144:145], off
	v_lshl_add_u64 v[166:167], v[136:137], 0, v[174:175]
	s_add_i32 m0, s2, 0x2000
	v_lshl_add_u64 v[238:239], v[136:137], 0, s[18:19]
	s_add_i32 s2, vcc_lo, s20
	global_load_lds_dwordx4 v[166:167], off
	v_lshl_add_u64 v[240:241], v[238:239], 0, v[164:165]
	s_mov_b32 m0, s2
	v_lshl_add_u64 v[238:239], v[238:239], 0, v[174:175]
	global_load_lds_dwordx4 v[240:241], off
	s_add_i32 m0, s2, 0x2000
	v_lshl_add_u64 v[240:241], s[86:87], 0, v[172:173]
	global_load_lds_dwordx4 v[238:239], off
	v_lshl_add_u64 v[238:239], s[86:87], 0, v[162:163]
	s_mov_b32 m0, s21
	s_nop 0
	global_load_lds_dwordx4 v[238:239], off
	s_mov_b32 m0, s23
	s_nop 0
	global_load_lds_dwordx4 v[240:241], off
	s_waitcnt vmcnt(8)
	s_waitcnt lgkmcnt(0)
	s_barrier
	s_setprio 1
	s_waitcnt lgkmcnt(0)
	v_mfma_f32_16x16x32_bf16 v[62:65], v[140:143], v[198:201], 0
	v_mfma_f32_16x16x32_bf16 v[58:61], v[154:157], v[198:201], 0
	v_mfma_f32_16x16x32_bf16 v[54:57], v[140:143], v[214:217], 0
	v_mfma_f32_16x16x32_bf16 v[50:53], v[154:157], v[214:217], 0
	v_mfma_f32_16x16x32_bf16 v[46:49], v[140:143], v[222:225], 0
	v_mfma_f32_16x16x32_bf16 v[42:45], v[154:157], v[222:225], 0
	v_mfma_f32_16x16x32_bf16 v[38:41], v[140:143], v[230:233], 0
	v_mfma_f32_16x16x32_bf16 v[34:37], v[154:157], v[230:233], 0
	v_mfma_f32_16x16x32_bf16 v[62:65], v[150:153], v[202:205], v[62:65]
	v_mfma_f32_16x16x32_bf16 v[58:61], v[158:161], v[202:205], v[58:61]
	v_mfma_f32_16x16x32_bf16 v[54:57], v[150:153], v[218:221], v[54:57]
	v_mfma_f32_16x16x32_bf16 v[50:53], v[158:161], v[218:221], v[50:53]
	v_mfma_f32_16x16x32_bf16 v[46:49], v[150:153], v[226:229], v[46:49]
	v_mfma_f32_16x16x32_bf16 v[42:45], v[158:161], v[226:229], v[42:45]
	v_mfma_f32_16x16x32_bf16 v[38:41], v[150:153], v[234:237], v[38:41]
	v_mfma_f32_16x16x32_bf16 v[34:37], v[158:161], v[234:237], v[34:37]
	s_setprio 0
	s_setprio 1
	v_mfma_f32_16x16x32_bf16 v[30:33], v[176:179], v[198:201], 0
	v_mfma_f32_16x16x32_bf16 v[26:29], v[184:187], v[198:201], 0
	v_mfma_f32_16x16x32_bf16 v[22:25], v[176:179], v[214:217], 0
	v_mfma_f32_16x16x32_bf16 v[18:21], v[184:187], v[214:217], 0
	v_mfma_f32_16x16x32_bf16 v[14:17], v[176:179], v[222:225], 0
	v_mfma_f32_16x16x32_bf16 v[10:13], v[184:187], v[222:225], 0
	v_mfma_f32_16x16x32_bf16 v[6:9], v[176:179], v[230:233], 0
	v_mfma_f32_16x16x32_bf16 v[2:5], v[184:187], v[230:233], 0
	v_mfma_f32_16x16x32_bf16 v[30:33], v[180:183], v[202:205], v[30:33]
	v_mfma_f32_16x16x32_bf16 v[26:29], v[194:197], v[202:205], v[26:29]
	v_mfma_f32_16x16x32_bf16 v[22:25], v[180:183], v[218:221], v[22:25]
	v_mfma_f32_16x16x32_bf16 v[18:21], v[194:197], v[218:221], v[18:21]
	v_mfma_f32_16x16x32_bf16 v[14:17], v[180:183], v[226:229], v[14:17]
	v_mfma_f32_16x16x32_bf16 v[10:13], v[194:197], v[226:229], v[10:13]
	v_mfma_f32_16x16x32_bf16 v[6:9], v[180:183], v[234:237], v[6:9]
	v_mfma_f32_16x16x32_bf16 v[2:5], v[194:197], v[234:237], v[2:5]
	s_setprio 0
	s_barrier
	s_add_i32 s16, 0, 0x18000
	v_add_u32_e32 v139, s16, v188
	s_add_i32 s73, 0, 0x1c000
	ds_read_b128 v[140:143], v139
	ds_read_b128 v[150:153], v139 offset:1024
	ds_read_b128 v[154:157], v139 offset:2048
	ds_read_b128 v[158:161], v139 offset:3072
	v_add_u32_e32 v139, s73, v188
	ds_read_b128 v[176:179], v139
	ds_read_b128 v[180:183], v139 offset:1024
	ds_read_b128 v[184:187], v139 offset:2048
	ds_read_b128 v[194:197], v139 offset:3072
	s_add_u32 s2, s86, 0x40000
	s_addc_u32 s3, s87, 0
	s_mov_b32 m0, s26
	v_lshl_add_u64 v[242:243], s[2:3], 0, v[162:163]
	ds_read_b128 v[198:201], v191 offset:32768
	ds_read_b128 v[202:205], v191 offset:33792
	ds_read_b128 v[214:217], v191 offset:34816
	ds_read_b128 v[218:221], v191 offset:35840
	ds_read_b128 v[222:225], v191 offset:36864
	ds_read_b128 v[226:229], v191 offset:37888
	ds_read_b128 v[230:233], v191 offset:38912
	ds_read_b128 v[234:237], v191 offset:39936
	global_load_lds_dwordx4 v[242:243], off
	v_lshl_add_u64 v[242:243], s[2:3], 0, v[172:173]
	s_mov_b32 m0, s27
	s_nop 0
	global_load_lds_dwordx4 v[242:243], off
	s_waitcnt vmcnt(8)
	s_waitcnt lgkmcnt(0)
	s_barrier
	s_setprio 1
	s_waitcnt lgkmcnt(0)
	v_mfma_f32_16x16x32_bf16 v[126:129], v[140:143], v[198:201], v[126:129]
	v_mfma_f32_16x16x32_bf16 v[122:125], v[154:157], v[198:201], v[122:125]
	v_mfma_f32_16x16x32_bf16 v[118:121], v[140:143], v[214:217], v[118:121]
	v_mfma_f32_16x16x32_bf16 v[114:117], v[154:157], v[214:217], v[114:117]
	v_mfma_f32_16x16x32_bf16 v[110:113], v[140:143], v[222:225], v[110:113]
	v_mfma_f32_16x16x32_bf16 v[106:109], v[154:157], v[222:225], v[106:109]
	v_mfma_f32_16x16x32_bf16 v[102:105], v[140:143], v[230:233], v[102:105]
	v_mfma_f32_16x16x32_bf16 v[98:101], v[154:157], v[230:233], v[98:101]
	v_mfma_f32_16x16x32_bf16 v[126:129], v[150:153], v[202:205], v[126:129]
	v_mfma_f32_16x16x32_bf16 v[122:125], v[158:161], v[202:205], v[122:125]
	v_mfma_f32_16x16x32_bf16 v[118:121], v[150:153], v[218:221], v[118:121]
	v_mfma_f32_16x16x32_bf16 v[114:117], v[158:161], v[218:221], v[114:117]
	v_mfma_f32_16x16x32_bf16 v[110:113], v[150:153], v[226:229], v[110:113]
	v_mfma_f32_16x16x32_bf16 v[106:109], v[158:161], v[226:229], v[106:109]
	v_mfma_f32_16x16x32_bf16 v[102:105], v[150:153], v[234:237], v[102:105]
	v_mfma_f32_16x16x32_bf16 v[98:101], v[158:161], v[234:237], v[98:101]
	s_setprio 0
	s_setprio 1
	v_mfma_f32_16x16x32_bf16 v[94:97], v[176:179], v[198:201], v[94:97]
	v_mfma_f32_16x16x32_bf16 v[90:93], v[184:187], v[198:201], v[90:93]
	v_mfma_f32_16x16x32_bf16 v[86:89], v[176:179], v[214:217], v[86:89]
	v_mfma_f32_16x16x32_bf16 v[82:85], v[184:187], v[214:217], v[82:85]
	v_mfma_f32_16x16x32_bf16 v[78:81], v[176:179], v[222:225], v[78:81]
	v_mfma_f32_16x16x32_bf16 v[74:77], v[184:187], v[222:225], v[74:77]
	v_mfma_f32_16x16x32_bf16 v[70:73], v[176:179], v[230:233], v[70:73]
	v_mfma_f32_16x16x32_bf16 v[66:69], v[184:187], v[230:233], v[66:69]
	v_mfma_f32_16x16x32_bf16 v[94:97], v[180:183], v[202:205], v[94:97]
	v_mfma_f32_16x16x32_bf16 v[90:93], v[194:197], v[202:205], v[90:93]
	v_mfma_f32_16x16x32_bf16 v[86:89], v[180:183], v[218:221], v[86:89]
	v_mfma_f32_16x16x32_bf16 v[82:85], v[194:197], v[218:221], v[82:85]
	v_mfma_f32_16x16x32_bf16 v[78:81], v[180:183], v[226:229], v[78:81]
	v_mfma_f32_16x16x32_bf16 v[74:77], v[194:197], v[226:229], v[74:77]
	v_mfma_f32_16x16x32_bf16 v[70:73], v[180:183], v[234:237], v[70:73]
	v_mfma_f32_16x16x32_bf16 v[66:69], v[194:197], v[234:237], v[66:69]
	s_setprio 0
	s_barrier
	s_add_i32 s2, s16, s20
	v_lshl_add_u64 v[144:145], v[144:145], 0, s[14:15]
	s_mov_b32 m0, s2
	ds_read_b128 v[198:201], v191 offset:49152
	ds_read_b128 v[202:205], v191 offset:50176
	ds_read_b128 v[214:217], v191 offset:51200
	ds_read_b128 v[218:221], v191 offset:52224
	ds_read_b128 v[222:225], v191 offset:53248
	ds_read_b128 v[226:229], v191 offset:54272
	ds_read_b128 v[230:233], v191 offset:55296
	ds_read_b128 v[234:237], v191 offset:56320
	global_load_lds_dwordx4 v[144:145], off
	s_add_i32 m0, s2, 0x2000
	s_mov_b64 s[2:3], 0x40080
	v_lshl_add_u64 v[144:145], v[166:167], 0, s[14:15]
	v_lshl_add_u64 v[136:137], v[136:137], 0, s[2:3]
	s_add_i32 s2, s73, s20
	global_load_lds_dwordx4 v[144:145], off
	v_lshl_add_u64 v[144:145], v[136:137], 0, v[164:165]
	s_mov_b32 m0, s2
	v_lshl_add_u64 v[136:137], v[136:137], 0, v[174:175]
	global_load_lds_dwordx4 v[144:145], off
	s_add_i32 m0, s2, 0x2000
	s_nop 0
	global_load_lds_dwordx4 v[136:137], off
	v_lshl_add_u64 v[136:137], v[238:239], 0, s[14:15]
	s_mov_b32 m0, s91
	s_nop 0
	global_load_lds_dwordx4 v[136:137], off
	v_lshl_add_u64 v[136:137], v[240:241], 0, s[14:15]
	s_mov_b32 m0, s92
	s_nop 0
	global_load_lds_dwordx4 v[136:137], off
	s_waitcnt vmcnt(8)
	s_waitcnt lgkmcnt(0)
	s_barrier
	s_setprio 1
	s_waitcnt lgkmcnt(0)
	v_mfma_f32_16x16x32_bf16 v[62:65], v[140:143], v[198:201], v[62:65]
	v_mfma_f32_16x16x32_bf16 v[58:61], v[154:157], v[198:201], v[58:61]
	v_mfma_f32_16x16x32_bf16 v[54:57], v[140:143], v[214:217], v[54:57]
	v_mfma_f32_16x16x32_bf16 v[50:53], v[154:157], v[214:217], v[50:53]
	v_mfma_f32_16x16x32_bf16 v[46:49], v[140:143], v[222:225], v[46:49]
	v_mfma_f32_16x16x32_bf16 v[42:45], v[154:157], v[222:225], v[42:45]
	v_mfma_f32_16x16x32_bf16 v[38:41], v[140:143], v[230:233], v[38:41]
	v_mfma_f32_16x16x32_bf16 v[34:37], v[154:157], v[230:233], v[34:37]
	v_mfma_f32_16x16x32_bf16 v[62:65], v[150:153], v[202:205], v[62:65]
	v_mfma_f32_16x16x32_bf16 v[58:61], v[158:161], v[202:205], v[58:61]
	v_mfma_f32_16x16x32_bf16 v[54:57], v[150:153], v[218:221], v[54:57]
	v_mfma_f32_16x16x32_bf16 v[50:53], v[158:161], v[218:221], v[50:53]
	v_mfma_f32_16x16x32_bf16 v[46:49], v[150:153], v[226:229], v[46:49]
	v_mfma_f32_16x16x32_bf16 v[42:45], v[158:161], v[226:229], v[42:45]
	v_mfma_f32_16x16x32_bf16 v[38:41], v[150:153], v[234:237], v[38:41]
	v_mfma_f32_16x16x32_bf16 v[34:37], v[158:161], v[234:237], v[34:37]
	s_setprio 0
	s_setprio 1
	v_mfma_f32_16x16x32_bf16 v[30:33], v[176:179], v[198:201], v[30:33]
	v_mfma_f32_16x16x32_bf16 v[26:29], v[184:187], v[198:201], v[26:29]
	v_mfma_f32_16x16x32_bf16 v[22:25], v[176:179], v[214:217], v[22:25]
	v_mfma_f32_16x16x32_bf16 v[18:21], v[184:187], v[214:217], v[18:21]
	v_mfma_f32_16x16x32_bf16 v[14:17], v[176:179], v[222:225], v[14:17]
	v_mfma_f32_16x16x32_bf16 v[10:13], v[184:187], v[222:225], v[10:13]
	v_mfma_f32_16x16x32_bf16 v[6:9], v[176:179], v[230:233], v[6:9]
	v_mfma_f32_16x16x32_bf16 v[2:5], v[184:187], v[230:233], v[2:5]
	v_mfma_f32_16x16x32_bf16 v[30:33], v[180:183], v[202:205], v[30:33]
	v_mfma_f32_16x16x32_bf16 v[26:29], v[194:197], v[202:205], v[26:29]
	v_mfma_f32_16x16x32_bf16 v[22:25], v[180:183], v[218:221], v[22:25]
	v_mfma_f32_16x16x32_bf16 v[18:21], v[194:197], v[218:221], v[18:21]
	v_mfma_f32_16x16x32_bf16 v[14:17], v[180:183], v[226:229], v[14:17]
	v_mfma_f32_16x16x32_bf16 v[10:13], v[194:197], v[226:229], v[10:13]
	v_mfma_f32_16x16x32_bf16 v[6:9], v[180:183], v[234:237], v[6:9]
	v_mfma_f32_16x16x32_bf16 v[2:5], v[194:197], v[234:237], v[2:5]
	s_setprio 0
	s_barrier
	s_mov_b32 s34, 2
